# GEMM1 tile order: original 3-row groups plus a per-group column rotation (21 columns per group) so no two XCDs walk the same weight panels at the same time
# baseline (speedup 1.0000x reference)
; #define LAS __attribute__((address_space(3)))
; __device__ __forceinline__ KP kargs() { KP q = (KP)__builtin_amdgcn_kernarg_segment_ptr(); asm volatile("" : "+s"(q)); return q; }
;     __device__ bool next(int i, Unit& u) const { if (i != 0) return false; u.pm = pm; u.pn = pn; return true; }
;     __device__ bool next(int i, Unit& u) const {
;         const long L = (long)i * G + c; if (L >= limit) return false;
;         int wgid = (int)L; { const int q = nwg / NXCD, r = nwg % NXCD, xcd = wgid % NXCD, off = wgid / NXCD; wgid = (xcd < r ? xcd * (q + 1) : r * (q + 1) + (xcd - r) * q) + off; }
;         const int nig = WGM * nN, gid = wgid / nig, fm = gid * WGM, gsz = (nM - fm) < WGM ? (nM - fm) : WGM;
;         u.pm = fm + ((wgid % nig) % gsz); u.pn = (wgid % nig) / gsz; return true;
; __global__ void __launch_bounds__(512, 2) fwd_megakernel(Params p_unused) {
;     ...
;     const int lo = kargs()->ph_lo, hi = kargs()->ph_hi;
;     volatile LAS unsigned* bst = (volatile LAS unsigned*)(lds + LDS_BYTES - 64);
;     if (threadIdx.x < 4) bst[threadIdx.x] = 0u;
;     __syncthreads();
;     XcdBarrier bar; bar.bar = (unsigned*)(kargs()->ws + WS_CTL); bar.x = xb_xcc_id(); bar.st = bst;
;     if (threadIdx.x == 0) bst[3] = xb_add(&bar.bar[XB_XCNT(bar.x)], 1u);
;     ...
;     if (lo < 0) grid.sync();
;     if (IN(0)) REPS(0) { phase_p0(kargs(), lds); }
;     SEAM(0);
;     if (IN(0) && IN(1)) {
;         if (threadIdx.x == 0) {
;             bool even = (bst[1] == 8u) && (gridDim.x % 8u == 0u);
;             for (unsigned j = 0; j < 16; ++j) { const unsigned c = xb_ld(&bar.bar[XB_XCNT(j)]); if (c != 0u && c != gridDim.x / 8u) even = false; }
;             bst[2] = even ? bst[3] * 8u + bar.x : blockIdx.x; }
;         __syncthreads();
;     } else if (threadIdx.x == 0) bst[2] = blockIdx.x;
;     __syncthreads();
;     const int vc = (int)bst[2];
;     for (int l = 0; l < DEPTH; ++l) {
;         const int pb = 1 + 6 * l; KP p = kargs(); unsigned char* ws = p->ws;
;         if (IN(pb + 0)) REPS(1) {
;             pg8::Gemm g{(const bf16_t*)(ws + WS_XB), (const bf16_t*)(ws + WS_WIN + l * SZ_WIN), SEQ, DIN, DM};
;             pg8::StaticOrder S; S.init(SEQ, DIN - 256, gridDim.x, vc);
;             pg8::EpiH E{(bf16_t*)(ws + WS_HM), (bf16_t*)(ws + WS_HG)};
;             pg8::gemm_phase<GEMM_ALIGN, GEMM_SP2>(lds, g, S, E);
.LBB0_212:
	s_add_i32 s3, 0, 0x23fc8
	v_mov_b32_e32 v0, s3
	s_waitcnt lgkmcnt(0)
	s_barrier
	ds_read_b32 v0, v0
	v_mov_b32_e32 v168, 1
	v_mov_b32_e32 v169, 0x3727c5ac
	v_mov_b64_e32 v[140:141], 0x1200
	v_mov_b64_e32 v[142:143], 0x11ff
	s_waitcnt lgkmcnt(0)
	v_readfirstlane_b32 s3, v0
	s_cmpk_lt_i32 s3, 0x1200
	s_cselect_b64 s[14:15], -1, 0
	s_ashr_i32 s13, s3, 31
	s_lshr_b32 s6, s13, 29
	s_add_i32 s6, s3, s6
	s_ashr_i32 s7, s6, 3
	s_and_b32 s6, s6, -8
	s_sub_i32 s6, s3, s6
	s_ashr_i32 s21, s72, 31
	s_add_u32 s48, s0, 0x3ab00200
	s_addc_u32 s49, s1, 0
	s_add_u32 s62, s0, 0x3ab00400
	s_addc_u32 s63, s1, 0
	s_add_u32 s64, s0, 0x3ab00500
	s_addc_u32 s65, s1, 0
	s_add_u32 s74, s0, 0x3ab00600
	s_addc_u32 s75, s1, 0
	s_add_u32 s10, s0, 0x3ab00700
	s_addc_u32 s11, s1, 0
	s_add_u32 s88, s0, 0x3ab00800
	s_addc_u32 s89, s1, 0
	s_add_u32 s94, s0, 0x3ab00900
	s_addc_u32 s95, s1, 0
	s_add_u32 s8, s0, 0x3ab00a00
	s_addc_u32 s9, s1, 0
	v_writelane_b32 v241, s8, 6
	v_mov_b32_e32 v170, 0x41f00000
	v_mov_b32_e32 v171, 0x4200
	v_writelane_b32 v241, s9, 7
	s_add_u32 s8, s0, 0x3ab00b00
	s_addc_u32 s9, s1, 0
	v_writelane_b32 v241, s8, 8
	v_mov_b32_e32 v173, 0xf149f2ca
	v_mov_b64_e32 v[144:145], 0x200
	v_writelane_b32 v241, s9, 9
	s_add_u32 s8, s0, 0x3ab00c00
	s_addc_u32 s9, s1, 0
	v_writelane_b32 v241, s8, 10
	v_mov_b64_e32 v[146:147], 0x1ff
	s_mov_b32 s51, 0x2aaaaaab
	v_writelane_b32 v241, s9, 11
	s_add_u32 s8, s0, 0x3ab00d00
	s_addc_u32 s9, s1, 0
	v_writelane_b32 v241, s8, 12
	s_movk_i32 s50, 0x4200
	s_movk_i32 s52, 0x3000
	v_writelane_b32 v241, s9, 13
	s_add_u32 s8, s0, 0x3ab00e00
	s_addc_u32 s9, s1, 0
	s_add_u32 s76, s0, 0x3ab00f00
	s_addc_u32 s77, s1, 0
	s_add_u32 s78, s0, 0x3ab01000
	s_addc_u32 s79, s1, 0
	s_add_u32 s80, s0, 0x3ab01100
	s_addc_u32 s81, s1, 0
	s_add_u32 s82, s0, 0x3ab01200
	s_addc_u32 s83, s1, 0
	s_add_u32 s84, s0, 0x3ab01300
	s_addc_u32 s85, s1, 0
	v_writelane_b32 v241, s8, 14
	s_cmp_eq_u32 s33, 15
	s_mov_b32 s54, 0xffff0000
	v_writelane_b32 v241, s9, 15
	s_cselect_b64 s[8:9], -1, 0
	v_writelane_b32 v241, s8, 16
	s_cmp_eq_u32 s33, 14
	s_movk_i32 s55, 0x2100
	v_writelane_b32 v241, s9, 17
	s_cselect_b64 s[8:9], -1, 0
	v_writelane_b32 v241, s8, 18
	s_cmp_eq_u32 s33, 13
	s_mov_b32 s56, 0x800000
	v_writelane_b32 v241, s9, 19
	s_cselect_b64 s[8:9], -1, 0
	v_writelane_b32 v241, s8, 20
	s_cmp_eq_u32 s33, 12
	s_mov_b32 s57, 0xffff
	v_writelane_b32 v241, s9, 21
	s_cselect_b64 s[8:9], -1, 0
	v_writelane_b32 v241, s8, 22
	s_cmp_eq_u32 s33, 11
	s_movk_i32 s58, 0x1ff
	v_writelane_b32 v241, s9, 23
	s_cselect_b64 s[8:9], -1, 0
	v_writelane_b32 v241, s8, 24
	s_cmp_eq_u32 s33, 10
	s_movk_i32 s67, 0x230
	v_writelane_b32 v241, s9, 25
	s_cselect_b64 s[8:9], -1, 0
	v_writelane_b32 v241, s8, 26
	s_cmp_eq_u32 s33, 9
	s_mov_b32 s59, 0x44000
	v_writelane_b32 v241, s9, 27
	s_cselect_b64 s[8:9], -1, 0
	v_writelane_b32 v241, s8, 28
	s_cmp_eq_u32 s33, 8
	s_mov_b32 s60, 0x5040100
	v_writelane_b32 v241, s9, 29
	s_cselect_b64 s[8:9], -1, 0
	v_writelane_b32 v241, s8, 30
	s_cmp_eq_u32 s33, 7
	s_mov_b64 s[16:17], 0x2000
	v_writelane_b32 v241, s9, 31
	s_cselect_b64 s[8:9], -1, 0
	v_writelane_b32 v241, s8, 32
	s_cmp_eq_u32 s33, 6
	s_mov_b64 s[18:19], 0x2a00
	v_writelane_b32 v241, s9, 33
	s_cselect_b64 s[8:9], -1, 0
	v_writelane_b32 v241, s8, 34
	s_cmp_eq_u32 s33, 5
	s_mov_b32 s20, 0x3fb504f3
	v_writelane_b32 v241, s9, 35
	s_cselect_b64 s[8:9], -1, 0
	v_writelane_b32 v241, s8, 36
	s_cmp_eq_u32 s33, 4
	s_nop 0
	v_writelane_b32 v241, s9, 37
	s_cselect_b64 s[8:9], -1, 0
	v_writelane_b32 v241, s8, 38
	s_cmp_eq_u32 s33, 3
	s_nop 0
	v_writelane_b32 v241, s9, 39
	s_cselect_b64 s[8:9], -1, 0
	v_writelane_b32 v241, s8, 40
	s_cmp_eq_u32 s33, 2
	s_nop 0
	v_writelane_b32 v241, s9, 41
	s_cselect_b64 s[8:9], -1, 0
	v_writelane_b32 v241, s8, 42
	s_cmp_eq_u32 s33, 1
	s_nop 0
	v_writelane_b32 v241, s9, 43
	s_cselect_b64 s[8:9], -1, 0
	v_writelane_b32 v241, s8, 44
	s_cmp_eq_u32 s33, 0
	s_nop 0
	v_writelane_b32 v241, s9, 45
	s_cselect_b64 s[8:9], -1, 0
	v_writelane_b32 v241, s8, 46
	s_nop 1
	v_writelane_b32 v241, s9, 47
	s_lshl_b32 s8, s33, 8
	s_add_u32 s8, s86, s8
	s_addc_u32 s9, s87, 0
	s_mov_b64 s[86:87], s[10:11]
	s_add_u32 s10, s8, 0x1400
	s_addc_u32 s11, s9, 0
	v_writelane_b32 v241, s10, 48
	s_add_u32 s8, s8, 0x2400
	s_addc_u32 s9, s9, 0
	v_writelane_b32 v241, s11, 49
;     __device__ bool next(int i, Unit& u) const { if (i != 0) return false; u.pm = pm; u.pn = pn; return true; }
;     __device__ bool next(int i, Unit& u) const { const int L = i * G + c; if (L >= 256) return false; u.pm = L; u.pn = L >> 6; return true; }
;     __device__ bool next(int i, Unit& u) const { Unit t; if (!so.next(i >> 2, t)) return false; const int b = i & 3; u.pm = b * 64 + t.pm; u.pn = b * 8 + t.pn; return true; }
;     __device__ bool next(int i, Unit& u) const {
;         const long L = (long)i * G + c; if (L >= limit) return false;
;         int wgid = (int)L; { const int q = nwg / NXCD, r = nwg % NXCD, xcd = wgid % NXCD, off = wgid / NXCD; wgid = (xcd < r ? xcd * (q + 1) : r * (q + 1) + (xcd - r) * q) + off; }
;         const int nig = WGM * nN, gid = wgid / nig, fm = gid * WGM, gsz = (nM - fm) < WGM ? (nM - fm) : WGM;
;         u.pm = fm + ((wgid % nig) % gsz); u.pn = (wgid % nig) / gsz; return true;
; __global__ void __launch_bounds__(512, 2) fwd_megakernel(Params p_unused) {
;     ...
;             pg8::StaticOrder S; S.init(SEQ, DIN - 256, gridDim.x, vc);
;     ...
;             pg8::BrOrder S; S.so.init(SEQ, DM, gridDim.x, vc);
	v_writelane_b32 v241, s8, 50
	s_movk_i32 s33, 0x2000
	s_nop 0
	v_writelane_b32 v241, s9, 51
	s_add_u32 s8, s0, 0x3ab03400
	s_addc_u32 s9, s1, 0
	v_writelane_b32 v241, s8, 52
	s_add_u32 s0, s0, 0x3ab03500
	s_addc_u32 s1, s1, 0
	v_writelane_b32 v241, s9, 53
	v_writelane_b32 v241, s0, 54
	s_nop 1
	v_writelane_b32 v241, s1, 55
	s_nop 0
	v_readlane_b32 s0, v241, 0
	v_readlane_b32 s1, v241, 1
	s_cmpk_lt_i32 s0, 0x100
	s_mov_b32 s8, s0
	s_cselect_b64 s[0:1], -1, 0
	v_writelane_b32 v241, s0, 56
	s_nop 1
	v_writelane_b32 v241, s1, 57
	s_ashr_i32 s1, s8, 31
	s_ashr_i32 s0, s8, 6
	v_writelane_b32 v241, s1, 58
	v_writelane_b32 v241, s0, 59
	s_ashr_i32 s0, s0, 31
	s_cmpk_lt_i32 s3, 0x200
	v_writelane_b32 v241, s0, 60
	s_cselect_b64 s[0:1], -1, 0
	v_writelane_b32 v241, s0, 61
	s_nop 1
	v_writelane_b32 v241, s1, 62
	s_lshl_b32 s1, s8, 3
	v_writelane_b32 v241, s1, 63
	s_lshl_b32 s1, s72, 3
	s_lshl_b32 s0, s6, 6
	v_writelane_b32 v240, s1, 0
	v_readlane_b32 s1, v241, 2
	s_cmp_gt_i32 s1, 7
	s_cselect_b64 s[8:9], -1, 0
	s_cmp_lt_i32 s6, 0
	s_movk_i32 s1, 0x241
	s_cselect_b32 s1, s1, 0x240
	s_mul_i32 s1, s6, s1
	s_mulk_i32 s6, 0x41
	s_cselect_b32 s0, s6, s0
	s_add_i32 s1, s1, s7
	v_writelane_b32 v240, s8, 1
	s_mul_hi_i32 s6, s1, 0x4bda12f7
	s_add_i32 s0, s0, s7
	v_writelane_b32 v240, s9, 2
	s_lshr_b32 s8, s6, 31
	s_ashr_i32 s6, s6, 6
	s_add_i32 s6, s6, s8
	s_mul_i32 s8, s6, 0xd8
	s_sub_i32 s8, s1, s8
	s_mul_hi_i32 s1, s0, 0x2aaaaaab
	s_lshr_b32 s7, s1, 31
	s_ashr_i32 s1, s1, 2
	s_add_i32 s1, s1, s7
	s_mul_i32 s7, s1, 24
	s_mul_i32 s6, s6, 3
	s_sub_i32 s7, s0, s7
	s_sub_i32 s0, 64, s6
	s_min_u32 s9, s0, 3
	v_cvt_f32_ubyte0_e32 v1, s9
	v_cvt_f32_i32_e32 v0, s8
	v_rcp_iflag_f32_e32 v2, v1
	s_mul_i32 s10, s1, 3
	s_sub_i32 s0, 64, s10
	s_min_u32 s11, s0, 3
	v_mul_f32_e32 v2, v0, v2
	v_trunc_f32_e32 v2, v2
	s_ashr_i32 s0, s8, 30
	v_fma_f32 v0, -v2, v1, v0
	s_or_b32 s12, s0, 1
	v_cmp_ge_f32_e64 s[0:1], |v0|, v1
	v_cvt_i32_f32_e32 v0, v2
	s_and_b64 s[0:1], s[0:1], exec
	v_cvt_f32_ubyte0_e32 v1, s11
	s_cselect_b32 s0, s12, 0
	v_readfirstlane_b32 s1, v0
	v_cvt_f32_i32_e32 v0, s7
	v_rcp_iflag_f32_e32 v2, v1
	s_add_i32 s12, s1, s0
	s_mul_i32 s0, s12, s9
	s_sub_i32 s0, s8, s0
	s_sext_i32_i16 s0, s0
	v_mul_f32_e32 v2, v0, v2
	s_add_i32 s0, s6, s0
	s_mul_i32 s1, s6, 7
	s_add_i32 s12, s12, s1
	s_mul_i32 s1, s12, 0x38f
	s_lshr_b32 s1, s1, 16
	s_mul_i32 s1, s1, 0x48
	s_sub_i32 s12, s12, s1
	v_trunc_f32_e32 v2, v2
	v_writelane_b32 v240, s0, 3
	s_ashr_i32 s0, s7, 30
	v_fma_f32 v0, -v2, v1, v0
	s_or_b32 s6, s0, 1
	v_cmp_ge_f32_e64 s[0:1], |v0|, v1
	v_cvt_i32_f32_e32 v0, v2
	s_and_b64 s[0:1], s[0:1], exec
	v_writelane_b32 v240, s14, 4
	s_mul_i32 s0, s73, s72
	s_mul_i32 s0, s0, s2
	v_writelane_b32 v240, s15, 5
	v_writelane_b32 v240, s0, 6
	s_cselect_b32 s0, s6, 0
	v_readfirstlane_b32 s1, v0
	s_add_i32 s0, s1, s0
	s_mul_i32 s1, s0, s11
	s_sub_i32 s1, s7, s1
	s_sext_i32_i8 s1, s1
	s_sext_i32_i16 s2, s12
	s_add_i32 s1, s10, s1
	v_writelane_b32 v240, s2, 7
	v_writelane_b32 v240, s1, 8
	s_ashr_i32 s1, s1, 31
	s_sext_i32_i8 s0, s0
	v_writelane_b32 v240, s1, 9
	v_writelane_b32 v240, s0, 10
	s_ashr_i32 s0, s0, 31
	v_writelane_b32 v240, s0, 11
	s_add_i32 s0, 0, 0x23fc0
	v_writelane_b32 v240, s0, 12
	s_add_i32 s0, 0, 0x23fc4
	v_writelane_b32 v240, s0, 13
	s_add_i32 s0, 0, 0x9200
	v_writelane_b32 v240, s0, 14
	s_add_i32 s0, 0, 0x12400
	v_writelane_b32 v240, s0, 15
	s_add_i32 s0, 0, 0x11c00
	v_writelane_b32 v240, s0, 16
	s_mov_b64 s[0:1], -1
	v_writelane_b32 v240, s0, 17
	v_mbcnt_lo_u32_b32 v0, -1, 0
	s_mov_b32 s7, 0
	v_writelane_b32 v240, s1, 18
	v_writelane_b32 v240, s48, 19
	v_cndmask_b32_e64 v167, 0, 1, s[14:15]
	v_mov_b32_e32 v1, 0
	v_writelane_b32 v240, s49, 20
	v_writelane_b32 v240, s62, 21
	v_mbcnt_hi_u32_b32 v172, -1, v0
	s_mov_b32 s73, 0xc1f00000
	v_writelane_b32 v240, s63, 22
	v_writelane_b32 v240, s64, 23
	s_movk_i32 s2, 0x1000
	s_add_i32 s53, 0, 0x23fe0
	v_writelane_b32 v240, s65, 24
	v_writelane_b32 v240, s74, 25
	s_mov_b64 s[8:9], 0x80
	s_mov_b64 s[10:11], 0x1000
	v_writelane_b32 v240, s75, 26
	v_writelane_b32 v240, s86, 27
	s_mov_b32 s12, 0x3a800000
	s_mov_b32 s6, s7
	v_writelane_b32 v240, s87, 28
	v_writelane_b32 v240, s88, 29
	s_nop 1
	v_writelane_b32 v240, s89, 30
	v_writelane_b32 v240, s94, 31
	s_nop 1
	v_writelane_b32 v240, s95, 32
	s_branch .LBB0_216

;     __device__ bool next(int i, Unit& u) const { if (i != 0) return false; u.pm = pm; u.pn = pn; return true; }
;     __device__ bool next(int i, Unit& u) const { const int L = i * G + c; if (L >= 256) return false; u.pm = L; u.pn = L >> 6; return true; }
;     __device__ bool next(int i, Unit& u) const { Unit t; if (!so.next(i >> 2, t)) return false; const int b = i & 3; u.pm = b * 64 + t.pm; u.pn = b * 8 + t.pn; return true; }
;     __device__ bool next(int i, Unit& u) const {
;         const long L = (long)i * G + c; if (L >= limit) return false;
;         int wgid = (int)L; { const int q = nwg / NXCD, r = nwg % NXCD, xcd = wgid % NXCD, off = wgid / NXCD; wgid = (xcd < r ? xcd * (q + 1) : r * (q + 1) + (xcd - r) * q) + off; }
;         const int nig = WGM * nN, gid = wgid / nig, fm = gid * WGM, gsz = (nM - fm) < WGM ? (nM - fm) : WGM;
;         u.pm = fm + ((wgid % nig) % gsz); u.pn = (wgid % nig) / gsz; return true;
; template <bool ALIGN_EPI, bool SP2, class Epi, class Sched>
; __device__ __forceinline__ void gemm_phase(LAS unsigned char* lds, const Gemm g, const Sched& S, const Epi& E) {
;     ...
;         const bool has_next = S.next(ui + 1, nxt);
.LBB0_227:
	s_add_i32 s66, s66, 1
	s_mul_i32 s24, s66, s21
	s_mul_hi_u32 s40, s66, s72
	s_add_i32 s24, s40, s24
	s_mul_i32 s40, s66, s72
	s_add_u32 s40, s40, s3
	s_addc_u32 s41, s24, s13
	v_cmp_gt_i64_e32 vcc, s[40:41], v[142:143]
	v_cmp_lt_i64_e64 s[42:43], s[40:41], v[140:141]
	s_cbranch_vccnz .LBB0_229
	s_ashr_i32 s24, s40, 31
	s_lshr_b32 s24, s24, 29
	s_add_i32 s24, s40, s24
	s_ashr_i32 s41, s24, 3
	s_and_b32 s24, s24, -8
	s_sub_i32 s24, s40, s24
	s_cmp_lt_i32 s24, 0
	s_cselect_b32 s40, s74, 0x240
	s_mul_i32 s24, s24, s40
	s_add_i32 s24, s24, s41
	s_mul_hi_i32 s40, s24, 0x4bda12f7
	s_lshr_b32 s41, s40, 31
	s_ashr_i32 s40, s40, 6
	s_add_i32 s40, s40, s41
	s_mul_i32 s41, s40, 3
	s_sub_i32 s48, 64, s41
	s_min_i32 s48, s48, 3
	s_abs_i32 s49, s48
	v_cvt_f32_u32_e32 v0, s49
	s_sub_i32 s68, 0, s49
	s_mulk_i32 s40, 0xd8
	s_sub_i32 s24, s24, s40
	v_rcp_iflag_f32_e32 v0, v0
	s_abs_i32 s40, s24
	s_xor_b32 s67, s24, s48
	s_ashr_i32 s67, s67, 31
	v_mul_f32_e32 v0, 0x4f7ffffe, v0
	v_cvt_u32_f32_e32 v0, v0
	s_nop 0
	v_readfirstlane_b32 s71, v0
	s_mul_i32 s68, s68, s71
	s_mul_hi_u32 s68, s71, s68
	s_add_i32 s71, s71, s68
	s_mul_hi_u32 s68, s40, s71
	s_mul_i32 s71, s68, s49
	s_sub_i32 s40, s40, s71
	s_add_i32 s86, s68, 1
	s_sub_i32 s71, s40, s49
	s_cmp_ge_u32 s40, s49
	s_cselect_b32 s68, s86, s68
	s_cselect_b32 s40, s71, s40
	s_add_i32 s71, s68, 1
	s_cmp_ge_u32 s40, s49
	s_cselect_b32 s40, s71, s68
	s_xor_b32 s40, s40, s67
	s_sub_i32 s67, s40, s67
	s_mul_i32 s40, s67, s48
	s_sub_i32 s24, s24, s40
	s_add_i32 s68, s41, s24
	s_mul_i32 s40, s41, 7
	s_add_i32 s67, s67, s40
	s_mul_i32 s40, s67, 0x38f
	s_lshr_b32 s40, s40, 16
	s_mul_i32 s40, s40, 0x48
	s_sub_i32 s67, s67, s40
